# SWA: a workgroup's 8 consecutive items are the 8 query heads of one kv head, K/V tiles staged into LDS once per 8 items (on top of v49)
# speedup vs baseline: 1.0040x; 1.0040x over previous
; template <bool MLA> __device__ __forceinline__ void attn_unit(const AttnP& P, int b, int hh, int qb, LAS char* lds) {
;     ...
;     const int q0 = qb * 256; const size_t rowbase = (size_t)b * SEQ;
;     const int jt0 = MLA ? 0 : (q0 == 0 ? 0 : -2);
;     const int NT = MLA ? 4 * qb + 4 : 4 - jt0;
;     const int kbase0 = MLA ? 0 : q0 + 64 * jt0;
;     const int qlo = q0 + wid * 32, qm = qlo + r32 - 4 * hi;
;     bf16x8 qr[NQF];
;     const size_t qrow = rowbase + qlo + r32;
;     if constexpr (MLA) {
; #pragma unroll
;         for (int d0 = 0; d0 < 8; ++d0) qr[d0] = *(const bf16x8*)(P.QN + qrow * 2048 + hh * 128 + d0 * 16 + hi * 8);
; #pragma unroll
;         for (int d0 = 0; d0 < 4; ++d0) qr[8 + d0] = *(const bf16x8*)(P.QR + qrow * 1024 + hh * 64 + d0 * 16 + hi * 8);
;     } else {
; #pragma unroll
;         for (int d0 = 0; d0 < 4; ++d0) qr[d0] = *(const bf16x8*)(P.QS + qrow * 2048 + hh * 64 + d0 * 16 + hi * 8);
;         if (tid < 128) bias_l[tid] = P.rel[(int)T5B[tid] * 32 + hh] * (1.0f / SCALE);
;     }
;     bf16x8 sk0, sv0;
;     const int sr8 = tid >> 3, ch8 = tid & 7;
;     const bf16_t* Kg; const bf16_t* Vg; const bf16_t* Rg = nullptr;
;     unsigned okA = 0, okB = 0, orp = 0, ovA = 0, ovB = 0;
;     if constexpr (MLA) {
;         Kg = P.KN + rowbase * 2048 + hh * 128; Vg = P.V + rowbase * 2048 + hh * 128; Rg = P.KR + rowbase * 64;
;         { const int rA = 4 * wid + (lane >> 4), rB = rA + 32, cp = lane & 15; okA = (unsigned)(rA * 2048 + ((cp ^ (rA & 7)) << 3)); okB = (unsigned)(rB * 2048 + ((cp ^ (rB & 7)) << 3)); }
;         { const int rr = 8 * wid + (lane >> 3), cp = lane & 7; orp = (unsigned)(rr * 64 + ((cp ^ (rr & 7)) << 3)); }
;         { const int stA = 2 * wid + (lane >> 5), stB = stA + 16; const int kl = (lane & 31) >> 2, c8 = 8 * (lane & 3);
;           const int kkA = (stA >> 2) * 8 + kl, kkB = (stB >> 2) * 8 + kl;
;           const int kA = (kkA & ~0xC) | ((kkA & 4) << 1) | ((kkA & 8) >> 1), kB = (kkB & ~0xC) | ((kkB & 4) << 1) | ((kkB & 8) >> 1);
;           ovA = (unsigned)(kA * 2048 + 32 * (stA & 3) + c8); ovB = (unsigned)(kB * 2048 + 32 * (stB & 3) + c8); }
;     } else { Kg = P.KS + (rowbase + sr8) * 256 + (hh >> 3) * 64 + ch8 * 8; Vg = P.VS + (rowbase + sr8) * 256 + (hh >> 3) * 64 + ch8 * 8; }
;     const int kws = KSWZ64(sr8, ch8), vst0 = v_st<NCB>(sr8, ch8 * 8);
.LBB0_600:
	v_readfirstlane_b32 s29, v162
	s_and_b32 s17, s2, 63
	s_ashr_i32 s36, s2, 11
	s_lshr_b32 s13, s29, 1
	s_lshl_b32 s28, s17, 8
	s_ashr_i32 s37, s36, 31
	s_and_b32 s16, s13, 0x7fffffe0
	s_bfe_u32 s15, s2, 0x20006
	s_bfe_u32 s33, s2, 0x30008
	s_lshl_b32 s15, s15, 3
	s_or_b32 s15, s15, s33
	s_lshl_b64 s[48:49], s[36:37], 14
	s_add_i32 s13, s16, s28
	s_add_u32 s46, s48, s13
	s_addc_u32 s47, s49, 0
	v_mov_b32_e32 v3, s47
	v_or_b32_e32 v2, s46, v90
	v_lshlrev_b64 v[2:3], 12, v[2:3]
	v_lshl_add_u64 v[2:3], s[18:19], 0, v[2:3]
	s_lshl_b32 s38, s15, 7
	v_lshl_add_u64 v[2:3], v[2:3], 0, s[38:39]
	v_lshl_add_u64 v[2:3], v[2:3], 0, v[92:93]
	global_load_dwordx4 v[66:69], v[2:3], off
	global_load_dwordx4 v[70:73], v[2:3], off offset:32
	global_load_dwordx4 v[74:77], v[2:3], off offset:64
	global_load_dwordx4 v[78:81], v[2:3], off offset:96
	s_lshl_b32 s14, s15, 6
	s_and_saveexec_b64 s[50:51], s[0:1]
	s_cbranch_execz .LBB0_602
	s_lshl_b32 s33, s15, 2
	v_lshl_or_b32 v2, v207, 7, s33
	global_load_dword v204, v2, s[70:71]
.LBB0_602:
	s_or_b64 exec, exec, s[50:51]
	s_and_b32 s29, s29, 0x3fffffc0
	s_and_b32 s35, s12, 63
	s_lshl_b32 s29, s29, 2
	s_lshr_b32 s33, s2, 6
	s_lshl_b32 s35, s35, 8
	s_add_i32 s36, s29, 0
	s_cmp_eq_u32 s17, 0
	v_mov_b32_e32 v3, s49
	v_or_b32_e32 v2, s48, v96
	s_cselect_b32 s37, 0, -2
	v_lshlrev_b64 v[2:3], 9, v[2:3]
	s_lshl_b32 s17, s33, 7
	s_lshl_b32 s40, s37, 6
	v_lshl_add_u64 v[4:5], s[58:59], 0, v[2:3]
	s_and_b32 s38, s17, 0x180
	s_add_i32 s28, s40, s28
	v_lshl_add_u64 v[4:5], v[4:5], 0, s[38:39]
	v_mov_b32_e32 v133, v93
	s_lshl_b32 s15, s15, 2
	v_lshl_add_u64 v[2:3], s[42:43], 0, v[2:3]
	v_lshl_add_u64 v[134:135], v[4:5], 0, v[132:133]
	v_mov_b32_e32 v4, s15
	v_lshl_add_u64 v[2:3], v[2:3], 0, s[38:39]
	s_ashr_i32 s29, s28, 31
	global_load_dword v18, v4, s[68:69]
	v_lshl_add_u64 v[136:137], v[2:3], 0, v[132:133]
	s_lshl_b64 s[28:29], s[28:29], 9
	v_lshl_add_u64 v[2:3], v[136:137], 0, s[28:29]
	v_lshl_add_u64 v[4:5], v[134:135], 0, s[28:29]
	s_bfe_u32 s100, s2, 0x30008
	s_cmp_eq_u32 s3, 0x100
	s_cselect_b32 s101, s100, 0
	s_cmp_lg_u32 s101, 0
	s_cbranch_scc1 .Lswa_ld_done
	global_load_dwordx4 v[182:185], v[2:3], off
	global_load_dwordx4 v[186:189], v[4:5], off
	v_lshl_add_u64 v[2:3], v[2:3], 0, s[98:99]
	v_lshl_add_u64 v[4:5], v[4:5], 0, s[98:99]
	global_load_dwordx4 v[190:193], v[2:3], off
	global_load_dwordx4 v[194:197], v[4:5], off
	v_lshl_add_u64 v[2:3], v[2:3], 0, s[98:99]
	v_lshl_add_u64 v[4:5], v[4:5], 0, s[98:99]
	global_load_dwordx4 v[208:211], v[2:3], off
	global_load_dwordx4 v[212:215], v[4:5], off
	v_lshl_add_u64 v[2:3], v[2:3], 0, s[98:99]
	v_lshl_add_u64 v[4:5], v[4:5], 0, s[98:99]
	global_load_dwordx4 v[216:219], v[2:3], off
	global_load_dwordx4 v[220:223], v[4:5], off
	s_cmp_eq_u32 s37, 0
	s_cbranch_scc1 .Lswa_ld_done
	v_lshl_add_u64 v[2:3], v[2:3], 0, s[98:99]
	v_lshl_add_u64 v[4:5], v[4:5], 0, s[98:99]
	global_load_dwordx4 v[224:227], v[2:3], off
	global_load_dwordx4 v[228:231], v[4:5], off
	v_lshl_add_u64 v[2:3], v[2:3], 0, s[98:99]
	v_lshl_add_u64 v[4:5], v[4:5], 0, s[98:99]
	global_load_dwordx4 v[232:235], v[2:3], off
	global_load_dwordx4 v[236:239], v[4:5], off
.Lswa_ld_done:
	v_add_u32_e32 v19, s16, v1
	v_mov_b32_e32 v16, v93
	v_mov_b32_e32 v17, v93
	s_waitcnt vmcnt(0)
	v_mov_b32_e32 v2, v93
	v_mov_b32_e32 v3, v93
	v_mov_b32_e32 v4, v93
	v_mov_b32_e32 v5, v93
	v_mov_b32_e32 v6, v93
	v_mov_b32_e32 v7, v93
	v_mov_b32_e32 v8, v93
	v_mov_b32_e32 v9, v93
	v_mov_b32_e32 v10, v93
	v_mov_b32_e32 v11, v93
	v_mov_b32_e32 v12, v93
	v_mov_b32_e32 v13, v93
	v_mov_b32_e32 v14, v93
	v_mov_b32_e32 v15, v93
	v_subrev_u32_e32 v150, s40, v19
	s_mov_b32 s15, 1
	v_mov_b32_e32 v152, 1.0
	v_lshl_add_u32 v131, v90, 2, s36
	v_lshl_add_u32 v133, v91, 2, s36
	s_or_b32 s16, s13, 31
	s_add_i32 s17, s13, 0xffffff81
	s_add_i32 s28, s13, 0xffffff9f
	s_sub_i32 s29, 4, s37
	s_add_i32 s33, s35, s40
	s_waitcnt vmcnt(0)
	s_and_saveexec_b64 s[50:51], s[0:1]
	v_mul_f32_e32 v204, 0x41000000, v204
	ds_write_b32 v97, v204 offset:34816
	s_or_b64 exec, exec, s[50:51]
	s_bfe_u32 s100, s2, 0x30008
	s_cmp_eq_u32 s3, 0x100
	s_cselect_b32 s101, s100, 0
	s_cmp_lg_u32 s101, 0
	s_cbranch_scc1 .Lswa_wr_done
	v_add_u32_e32 v34, 0x9000, v140
	v_add_u32_e32 v35, 0x9000, v141
	ds_write_b128 v34, v[182:185] offset:16384
	ds_write_b128 v35, v[186:189]
	v_add_u32_e32 v34, 0xb000, v140
	v_add_u32_e32 v35, 0xb000, v141
	ds_write_b128 v34, v[190:193] offset:16384
	ds_write_b128 v35, v[194:197]
	v_add_u32_e32 v34, 0x11000, v140
	v_add_u32_e32 v35, 0x11000, v141
	ds_write_b128 v34, v[208:211] offset:16384
	ds_write_b128 v35, v[212:215]
	v_add_u32_e32 v34, 0x13000, v140
	v_add_u32_e32 v35, 0x13000, v141
	ds_write_b128 v34, v[216:219] offset:16384
	ds_write_b128 v35, v[220:223]
	s_cmp_eq_u32 s37, 0
	s_cbranch_scc1 .Lswa_wr_done
	v_add_u32_e32 v34, 0x19000, v140
	v_add_u32_e32 v35, 0x19000, v141
	ds_write_b128 v34, v[224:227] offset:16384
	ds_write_b128 v35, v[228:231]
	v_add_u32_e32 v34, 0x1b000, v140
	v_add_u32_e32 v35, 0x1b000, v141
	ds_write_b128 v34, v[232:235] offset:16384
	ds_write_b128 v35, v[236:239]
